# P0: silu-vector and MOD-row LDS fills issue all 12 loads before waiting
# speedup vs baseline: 1.0101x; 1.0101x over previous
.LBB0_11:
	v_add_u32_e32 v2, 0x1000, v1
	v_add_u32_e32 v3, 0x2000, v1
	v_add_u32_e32 v5, 0x3000, v1
	global_load_dword v10, v1, s[12:13]
	global_load_dword v11, v1, s[12:13] offset:2048
	global_load_dword v12, v2, s[12:13]
	global_load_dword v13, v2, s[12:13] offset:2048
	global_load_dword v14, v1, s[14:15]
	global_load_dword v15, v1, s[14:15] offset:2048
	global_load_dword v16, v2, s[14:15]
	global_load_dword v17, v2, s[14:15] offset:2048
	global_load_dword v18, v3, s[14:15]
	global_load_dword v19, v3, s[14:15] offset:2048
	global_load_dword v20, v5, s[14:15]
	global_load_dword v21, v5, s[14:15] offset:2048
	s_waitcnt vmcnt(0)
	v_mul_f32_e32 v22, 0xbfb8aa3b, v10
	v_mul_f32_e32 v23, 0xbfb8aa3b, v11
	v_mul_f32_e32 v24, 0xbfb8aa3b, v12
	v_mul_f32_e32 v25, 0xbfb8aa3b, v13
	v_mul_f32_e32 v26, 0xbfb8aa3b, v14
	v_mul_f32_e32 v27, 0xbfb8aa3b, v15
	v_mul_f32_e32 v28, 0xbfb8aa3b, v16
	v_mul_f32_e32 v29, 0xbfb8aa3b, v17
	v_mul_f32_e32 v30, 0xbfb8aa3b, v18
	v_mul_f32_e32 v31, 0xbfb8aa3b, v19
	v_mul_f32_e32 v32, 0xbfb8aa3b, v20
	v_mul_f32_e32 v33, 0xbfb8aa3b, v21
	v_exp_f32_e32 v22, v22
	v_exp_f32_e32 v23, v23
	v_exp_f32_e32 v24, v24
	v_exp_f32_e32 v25, v25
	v_exp_f32_e32 v26, v26
	v_exp_f32_e32 v27, v27
	v_exp_f32_e32 v28, v28
	v_exp_f32_e32 v29, v29
	v_exp_f32_e32 v30, v30
	v_exp_f32_e32 v31, v31
	v_exp_f32_e32 v32, v32
	v_exp_f32_e32 v33, v33
	v_add_f32_e32 v22, 1.0, v22
	v_add_f32_e32 v23, 1.0, v23
	v_add_f32_e32 v24, 1.0, v24
	v_add_f32_e32 v25, 1.0, v25
	v_add_f32_e32 v26, 1.0, v26
	v_add_f32_e32 v27, 1.0, v27
	v_add_f32_e32 v28, 1.0, v28
	v_add_f32_e32 v29, 1.0, v29
	v_add_f32_e32 v30, 1.0, v30
	v_add_f32_e32 v31, 1.0, v31
	v_add_f32_e32 v32, 1.0, v32
	v_add_f32_e32 v33, 1.0, v33
	v_rcp_f32_e32 v22, v22
	v_rcp_f32_e32 v23, v23
	v_rcp_f32_e32 v24, v24
	v_rcp_f32_e32 v25, v25
	v_rcp_f32_e32 v26, v26
	v_rcp_f32_e32 v27, v27
	v_rcp_f32_e32 v28, v28
	v_rcp_f32_e32 v29, v29
	v_rcp_f32_e32 v30, v30
	v_rcp_f32_e32 v31, v31
	v_rcp_f32_e32 v32, v32
	v_rcp_f32_e32 v33, v33
	v_mul_f32_e32 v10, v10, v22
	v_mul_f32_e32 v11, v11, v23
	v_mul_f32_e32 v12, v12, v24
	v_mul_f32_e32 v13, v13, v25
	v_mul_f32_e32 v14, v14, v26
	v_mul_f32_e32 v15, v15, v27
	v_mul_f32_e32 v16, v16, v28
	v_mul_f32_e32 v17, v17, v29
	v_mul_f32_e32 v18, v18, v30
	v_mul_f32_e32 v19, v19, v31
	v_mul_f32_e32 v20, v20, v32
	v_mul_f32_e32 v21, v21, v33
	ds_write_b32 v4, v10
	ds_write_b32 v4, v11 offset:2048
	ds_write_b32 v4, v12 offset:4096
	ds_write_b32 v4, v13 offset:6144
	ds_write_b32 v4, v14 offset:8192
	ds_write_b32 v4, v15 offset:10240
	ds_write_b32 v4, v16 offset:12288
	ds_write_b32 v4, v17 offset:14336
	ds_write_b32 v4, v18 offset:16384
	ds_write_b32 v4, v19 offset:18432
	ds_write_b32 v4, v20 offset:20480
	ds_write_b32 v4, v21 offset:22528
	s_or_b64 exec, exec, s[0:1]
	v_readlane_b32 s0, v252, 2
	s_cmpk_gt_i32 s0, 0xbf
	s_waitcnt lgkmcnt(0)
	s_barrier
	s_cbranch_scc1 .LBB0_21
	v_lshrrev_b32_e32 v6, 4, v50
	v_lshl_or_b32 v2, s64, 7, v6
	s_movk_i32 s14, 0x6000
	s_add_u32 s8, s46, 0x100000
	v_mad_u64_u32 v[2:3], s[0:1], v2, s14, 0
	s_addc_u32 s9, s47, 0
	s_lshl_b32 s0, s64, 9
	s_add_i32 s0, s0, 0
	v_and_b32_e32 v4, 60, v1
	v_lshl_add_u32 v1, v6, 2, s0
	v_mbcnt_lo_u32_b32 v6, -1, 0
	v_mbcnt_hi_u32_b32 v6, -1, v6
	v_and_b32_e32 v8, 64, v6
	v_xor_b32_e32 v7, 16, v6
	v_add_u32_e32 v8, 64, v8
	v_cmp_lt_i32_e32 vcc, v7, v8
	v_lshl_add_u32 v61, v50, 4, 0
	v_mov_b32_e32 v5, 0
	v_cndmask_b32_e32 v7, v6, v7, vcc
	v_lshlrev_b32_e32 v51, 2, v7
	v_xor_b32_e32 v7, 32, v6
	v_cmp_lt_i32_e32 vcc, v7, v8
	s_movk_i32 s0, 0x180
	v_mad_i32_i24 v10, v50, -12, v61
	v_cndmask_b32_e32 v6, v6, v7, vcc
	v_lshlrev_b32_e32 v60, 2, v6
	v_lshrrev_b32_e32 v6, 6, v0
	v_lshlrev_b32_e32 v11, 8, v6
	v_cmp_gt_u32_e32 vcc, 16, v50
	v_cmp_gt_u32_e64 s[4:5], s0, v0
	v_mov_b32_e32 v7, v5
	s_mul_i32 s15, s64, 0x600
	v_lshlrev_b32_e32 v8, 2, v4
	v_mov_b32_e32 v9, v5
	s_mov_b32 s28, 0x18000
	s_mov_b32 s29, 0x30000
	s_mov_b32 s30, 0x48000
	s_mov_b32 s31, 0x60000
	s_mov_b32 s34, 0x78000
	s_mov_b32 s35, 0x90000
	s_mov_b32 s36, 0xa8000
	v_add_u32_e32 v62, v10, v11
	v_lshlrev_b32_e32 v4, 2, v50
	v_readlane_b32 s37, v252, 2
	s_branch .LBB0_15

.LBB0_211:
	s_mul_i32 s28, s38, 0x6000
	v_lshlrev_b32_e32 v12, 2, v0
	v_add_u32_e32 v12, s28, v12
	v_add_u32_e32 v13, 0x6000, v12
	v_add_u32_e32 v14, 0xc000, v12
	v_add_u32_e32 v15, 0x12000, v12
	v_add_u32_e32 v16, 0x18000, v12
	v_add_u32_e32 v17, 0x1e000, v12
	v_readfirstlane_b32 s28, v2
	v_readfirstlane_b32 s29, v3
	s_nop 4
	global_load_dword v22, v12, s[28:29]
	global_load_dword v23, v12, s[28:29] offset:2048
	global_load_dword v24, v13, s[28:29]
	global_load_dword v25, v13, s[28:29] offset:2048
	global_load_dword v26, v14, s[28:29]
	global_load_dword v27, v14, s[28:29] offset:2048
	global_load_dword v28, v15, s[28:29]
	global_load_dword v29, v15, s[28:29] offset:2048
	global_load_dword v30, v16, s[28:29]
	global_load_dword v31, v16, s[28:29] offset:2048
	global_load_dword v32, v17, s[28:29]
	global_load_dword v33, v17, s[28:29] offset:2048
	s_waitcnt vmcnt(0)
	ds_write_b32 v4, v22
	ds_write_b32 v4, v23 offset:2048
	ds_write_b32 v4, v24 offset:4096
	ds_write_b32 v4, v25 offset:6144
	ds_write_b32 v4, v26 offset:8192
	ds_write_b32 v4, v27 offset:10240
	ds_write_b32 v4, v28 offset:12288
	ds_write_b32 v4, v29 offset:14336
	ds_write_b32 v4, v30 offset:16384
	ds_write_b32 v4, v31 offset:18432
	ds_write_b32 v4, v32 offset:20480
	ds_write_b32 v4, v33 offset:22528
	s_or_b64 exec, exec, s[26:27]
	s_ashr_i32 s23, s22, 31
	s_mov_b64 s[28:29], -1
	s_and_b64 vcc, exec, s[16:17]
	s_waitcnt lgkmcnt(0)
	s_barrier
	s_cbranch_vccz .LBB0_214
	s_lshl_b64 s[26:27], s[22:23], 24
	s_add_u32 s26, s92, s26
	s_addc_u32 s27, s93, s27
	s_mov_b64 s[28:29], 0
